# code placement: fast attention loop moved by 4 bytes (head at 0 mod 8 instead of 4 mod 8); later code placement unchanged mod 8
# speedup vs baseline: 1.0071x; 1.0071x over previous
.LBB0_393:
	s_add_i32 s20, s44, 0x2000
	s_cmpk_lg_i32 s44, 0x4000
	s_cselect_b32 s21, s20, 0
	s_add_i32 s41, s41, 2
	s_mov_b64 s[30:31], 0x4000
	s_cmp_lt_u32 s41, 57
	v_lshl_add_u64 v[180:181], v[180:181], 0, s[30:31]
	s_cbranch_scc0 .LBB0_401
	s_mov_b32 s20, s42
	s_mov_b32 s43, s44
	s_mov_b32 s42, s21
	s_branch .LBB0_387
	s_nop 0
.Lattn_fast_top:
	v_add_u32_e32 v185, s20, v224
	ds_read_b64_tr_b16 v[176:177], v185 offset:24576
	ds_read_b64_tr_b16 v[178:179], v185 offset:25088
	v_mfma_f32_32x32x16_bf16 v[96:111], v[80:83], v[156:159], v[32:47]
	v_add_f32_e32 v84, v64, v65
	v_add_f32_e32 v84, v66, v84
	v_add_f32_e32 v84, v67, v84
	v_add_f32_e32 v84, v68, v84
	v_add_f32_e32 v84, v69, v84
	v_cvt_pk_bf16_f32 v148, v64, v65
	v_cvt_pk_bf16_f32 v149, v66, v67
	ds_read_b64_tr_b16 v[172:173], v185 offset:28672
	ds_read_b64_tr_b16 v[174:175], v185 offset:29184
	v_add_f32_e32 v64, v70, v84
	v_mfma_f32_32x32x16_bf16 v[80:95], v[164:167], v[156:159], v[32:47]
	v_add_f32_e32 v64, v71, v64
	v_add_f32_e32 v64, v72, v64
	v_add_f32_e32 v128, v73, v64
	v_cvt_pk_bf16_f32 v150, v68, v69
	v_cvt_pk_bf16_f32 v151, v70, v71
	ds_read_b64_tr_b16 v[64:65], v185 offset:25600
	ds_read_b64_tr_b16 v[66:67], v185 offset:26112
	v_mfma_f32_32x32x16_bf16 v[96:111], v[168:171], v[152:155], v[96:111]
	v_add_f32_e32 v68, v74, v128
	v_add_f32_e32 v68, v75, v68
	v_add_f32_e32 v68, v76, v68
	v_add_f32_e32 v128, v77, v68
	v_cvt_pk_bf16_f32 v144, v72, v73
	v_cvt_pk_bf16_f32 v145, v74, v75
	ds_read_b64_tr_b16 v[68:69], v185 offset:29696
	ds_read_b64_tr_b16 v[70:71], v185 offset:30208
	v_mfma_f32_32x32x16_bf16 v[80:95], v[160:163], v[152:155], v[80:95]
	v_add_f32_e32 v72, v78, v128
	v_add_f32_e32 v72, v79, v72
	v_add_f32_e32 v72, v48, v72
	v_add_f32_e32 v128, v49, v72
	v_cvt_pk_bf16_f32 v146, v76, v77
	v_cvt_pk_bf16_f32 v147, v78, v79
	ds_read_b64_tr_b16 v[72:73], v185 offset:26624
	ds_read_b64_tr_b16 v[74:75], v185 offset:27136
	v_mfma_f32_32x32x16_bf16 v[96:111], v[124:127], v[140:143], v[96:111]
	v_add_f32_e32 v76, v50, v128
	v_add_f32_e32 v76, v51, v76
	v_add_f32_e32 v76, v52, v76
	v_add_f32_e32 v76, v53, v76
	v_cvt_pk_bf16_f32 v136, v48, v49
	v_cvt_pk_bf16_f32 v137, v50, v51
	ds_read_b64_tr_b16 v[48:49], v185 offset:30720
	ds_read_b64_tr_b16 v[50:51], v185 offset:31232
	v_mfma_f32_32x32x16_bf16 v[80:95], v[120:123], v[140:143], v[80:95]
	v_add_f32_e32 v76, v54, v76
	v_add_f32_e32 v76, v55, v76
	v_add_f32_e32 v76, v56, v76
	v_add_f32_e32 v76, v57, v76
	v_cvt_pk_bf16_f32 v138, v52, v53
	v_cvt_pk_bf16_f32 v139, v54, v55
	ds_read_b64_tr_b16 v[52:53], v185 offset:27648
	ds_read_b64_tr_b16 v[54:55], v185 offset:28160
	v_mfma_f32_32x32x16_bf16 v[96:111], v[116:119], v[132:135], v[96:111]
	v_add_f32_e32 v76, v58, v76
	v_add_f32_e32 v76, v59, v76
	v_add_f32_e32 v76, v60, v76
	v_add_f32_e32 v76, v61, v76
	v_cvt_pk_bf16_f32 v128, v56, v57
	v_cvt_pk_bf16_f32 v129, v58, v59
	ds_read_b64_tr_b16 v[56:57], v185 offset:31744
	ds_read_b64_tr_b16 v[58:59], v185 offset:32256
	v_mfma_f32_32x32x16_bf16 v[80:95], v[112:115], v[132:135], v[80:95]
	v_add_f32_e32 v76, v62, v76
	v_add_f32_e32 v76, v63, v76
	v_cvt_pk_bf16_f32 v130, v60, v61
	v_cvt_pk_bf16_f32 v131, v62, v63
	s_mov_b64 s[20:21], 0x6000
	v_lshl_add_u64 v[60:61], v[180:181], 0, s[20:21]
	s_add_i32 m0, s43, s39
	s_nop 0
	global_load_lds_dwordx4 v[60:61], off
	v_lshl_add_u64 v[60:61], v[182:183], 0, s[48:49]
	s_add_i32 m0, s42, s35
	s_nop 0
	global_load_lds_dwordx4 v[60:61], off
	v_add_f32_e32 v184, v184, v76
	s_waitcnt lgkmcnt(14)
	v_mfma_f32_32x32x16_bf16 v[0:15], v[148:151], v[176:179], v[0:15]
	v_exp_f32_e32 v96, v96
	v_exp_f32_e32 v97, v97
	v_exp_f32_e32 v98, v98
	v_exp_f32_e32 v99, v99
	s_waitcnt lgkmcnt(12)
	v_mfma_f32_32x32x16_bf16 v[16:31], v[148:151], v[172:175], v[16:31]
	v_exp_f32_e32 v100, v100
	v_exp_f32_e32 v101, v101
	v_exp_f32_e32 v102, v102
	v_exp_f32_e32 v103, v103
	v_add_u32_e32 v76, s42, v225
	ds_read_b128 v[60:63], v76
	ds_read_b128 v[172:175], v76 offset:512
	s_waitcnt lgkmcnt(12)
	v_mfma_f32_32x32x16_bf16 v[0:15], v[144:147], v[64:67], v[0:15]
	v_exp_f32_e32 v104, v104
	v_exp_f32_e32 v105, v105
	v_exp_f32_e32 v106, v106
	v_exp_f32_e32 v107, v107
	ds_read_b128 v[176:179], v76 offset:2048
	ds_read_b128 v[168:171], v76 offset:2560
	s_waitcnt lgkmcnt(12)
	v_mfma_f32_32x32x16_bf16 v[16:31], v[144:147], v[68:71], v[16:31]
	v_exp_f32_e32 v108, v108
	v_exp_f32_e32 v109, v109
	v_exp_f32_e32 v110, v110
	v_exp_f32_e32 v111, v111
	ds_read_b128 v[164:167], v76 offset:4096
	ds_read_b128 v[160:163], v76 offset:4608
	s_waitcnt lgkmcnt(12)
	v_mfma_f32_32x32x16_bf16 v[0:15], v[136:139], v[72:75], v[0:15]
	v_exp_f32_e32 v80, v80
	v_exp_f32_e32 v81, v81
	v_exp_f32_e32 v82, v82
	v_exp_f32_e32 v83, v83
	ds_read_b128 v[124:127], v76 offset:6144
	ds_read_b128 v[120:123], v76 offset:6656
	s_waitcnt lgkmcnt(12)
	v_mfma_f32_32x32x16_bf16 v[16:31], v[136:139], v[48:51], v[16:31]
	v_exp_f32_e32 v84, v84
	v_exp_f32_e32 v85, v85
	v_exp_f32_e32 v86, v86
	v_exp_f32_e32 v87, v87
	s_waitcnt lgkmcnt(10)
	v_mfma_f32_32x32x16_bf16 v[0:15], v[128:131], v[52:55], v[0:15]
	v_exp_f32_e32 v88, v88
	v_exp_f32_e32 v89, v89
	v_exp_f32_e32 v90, v90
	v_exp_f32_e32 v91, v91
	s_waitcnt lgkmcnt(8)
	v_mfma_f32_32x32x16_bf16 v[16:31], v[128:131], v[56:59], v[16:31]
	v_exp_f32_e32 v92, v92
	v_exp_f32_e32 v93, v93
	v_exp_f32_e32 v94, v94
	v_exp_f32_e32 v95, v95
	s_waitcnt vmcnt(2) lgkmcnt(0)
	s_barrier
	s_add_i32 s20, s42, 0x2000
	s_cmpk_lg_i32 s42, 0x4000
	s_cselect_b32 s44, s20, 0
	v_add_u32_e32 v185, s43, v224
	ds_read_b64_tr_b16 v[116:117], v185 offset:24576
	ds_read_b64_tr_b16 v[118:119], v185 offset:25088
	v_mfma_f32_32x32x16_bf16 v[64:79], v[60:63], v[156:159], v[32:47]
	v_add_f32_e32 v48, v96, v97
	v_add_f32_e32 v48, v98, v48
	v_add_f32_e32 v48, v99, v48
	v_add_f32_e32 v48, v100, v48
	v_add_f32_e32 v48, v101, v48
	v_cvt_pk_bf16_f32 v148, v96, v97
	v_cvt_pk_bf16_f32 v149, v98, v99
	ds_read_b64_tr_b16 v[112:113], v185 offset:28672
	ds_read_b64_tr_b16 v[114:115], v185 offset:29184
	v_add_f32_e32 v48, v102, v48
	v_add_f32_e32 v48, v103, v48
	v_add_f32_e32 v48, v104, v48
	v_add_f32_e32 v128, v105, v48
	v_mfma_f32_32x32x16_bf16 v[48:63], v[172:175], v[156:159], v[32:47]
	v_cvt_pk_bf16_f32 v150, v100, v101
	v_cvt_pk_bf16_f32 v151, v102, v103
	ds_read_b64_tr_b16 v[96:97], v185 offset:25600
	ds_read_b64_tr_b16 v[98:99], v185 offset:26112
	v_mfma_f32_32x32x16_bf16 v[64:79], v[176:179], v[152:155], v[64:79]
	v_add_f32_e32 v100, v106, v128
	v_add_f32_e32 v100, v107, v100
	v_add_f32_e32 v100, v108, v100
	v_add_f32_e32 v128, v109, v100
	v_cvt_pk_bf16_f32 v144, v104, v105
	v_cvt_pk_bf16_f32 v145, v106, v107
	ds_read_b64_tr_b16 v[100:101], v185 offset:29696
	ds_read_b64_tr_b16 v[102:103], v185 offset:30208
	v_mfma_f32_32x32x16_bf16 v[48:63], v[168:171], v[152:155], v[48:63]
	v_add_f32_e32 v104, v110, v128
	v_add_f32_e32 v104, v111, v104
	v_add_f32_e32 v104, v80, v104
	v_add_f32_e32 v128, v81, v104
	v_cvt_pk_bf16_f32 v146, v108, v109
	v_cvt_pk_bf16_f32 v147, v110, v111
	ds_read_b64_tr_b16 v[104:105], v185 offset:26624
	ds_read_b64_tr_b16 v[106:107], v185 offset:27136
	v_mfma_f32_32x32x16_bf16 v[64:79], v[164:167], v[140:143], v[64:79]
	v_add_f32_e32 v108, v82, v128
	v_add_f32_e32 v108, v83, v108
	v_add_f32_e32 v108, v84, v108
	v_add_f32_e32 v128, v85, v108
	v_cvt_pk_bf16_f32 v136, v80, v81
	v_cvt_pk_bf16_f32 v137, v82, v83
	ds_read_b64_tr_b16 v[108:109], v185 offset:30720
	ds_read_b64_tr_b16 v[110:111], v185 offset:31232
	v_mfma_f32_32x32x16_bf16 v[48:63], v[160:163], v[140:143], v[48:63]
	v_add_f32_e32 v80, v86, v128
	v_add_f32_e32 v80, v87, v80
	v_add_f32_e32 v80, v88, v80
	v_add_f32_e32 v80, v89, v80
	v_cvt_pk_bf16_f32 v138, v84, v85
	v_cvt_pk_bf16_f32 v139, v86, v87
	ds_read_b64_tr_b16 v[84:85], v185 offset:27648
	ds_read_b64_tr_b16 v[86:87], v185 offset:28160
	v_mfma_f32_32x32x16_bf16 v[64:79], v[124:127], v[132:135], v[64:79]
	v_add_f32_e32 v80, v90, v80
	v_add_f32_e32 v80, v91, v80
	v_add_f32_e32 v80, v92, v80
	v_add_f32_e32 v80, v93, v80
	v_cvt_pk_bf16_f32 v128, v88, v89
	v_cvt_pk_bf16_f32 v129, v90, v91
	ds_read_b64_tr_b16 v[88:89], v185 offset:31744
	ds_read_b64_tr_b16 v[90:91], v185 offset:32256
	v_mfma_f32_32x32x16_bf16 v[48:63], v[120:123], v[132:135], v[48:63]
	v_add_f32_e32 v80, v94, v80
	v_add_f32_e32 v80, v95, v80
	v_add_f32_e32 v82, 0, v80
	v_cvt_pk_bf16_f32 v130, v92, v93
	v_cvt_pk_bf16_f32 v131, v94, v95
	v_lshl_add_u64 v[80:81], v[180:181], 0, s[88:89]
	s_add_i32 m0, s42, s39
	s_nop 0
	global_load_lds_dwordx4 v[80:81], off
	s_mov_b64 s[20:21], 0x4000
	v_lshl_add_u64 v[182:183], v[182:183], 0, s[20:21]
	s_add_i32 m0, s44, s35
	s_nop 0
	global_load_lds_dwordx4 v[182:183], off
	v_add_f32_e32 v184, v184, v82
	s_waitcnt lgkmcnt(14)
	v_mfma_f32_32x32x16_bf16 v[0:15], v[148:151], v[116:119], v[0:15]
	v_exp_f32_e32 v64, v64
	v_exp_f32_e32 v65, v65
	v_exp_f32_e32 v66, v66
	v_exp_f32_e32 v67, v67
	s_waitcnt lgkmcnt(12)
	v_mfma_f32_32x32x16_bf16 v[16:31], v[148:151], v[112:115], v[16:31]
	v_exp_f32_e32 v68, v68
	v_exp_f32_e32 v69, v69
	v_exp_f32_e32 v70, v70
	v_exp_f32_e32 v71, v71
	v_add_u32_e32 v92, s44, v225
	ds_read_b128 v[80:83], v92
	ds_read_b128 v[164:167], v92 offset:512
	s_waitcnt lgkmcnt(12)
	v_mfma_f32_32x32x16_bf16 v[0:15], v[144:147], v[96:99], v[0:15]
	v_exp_f32_e32 v72, v72
	v_exp_f32_e32 v73, v73
	v_exp_f32_e32 v74, v74
	v_exp_f32_e32 v75, v75
	ds_read_b128 v[168:171], v92 offset:2048
	ds_read_b128 v[160:163], v92 offset:2560
	s_waitcnt lgkmcnt(12)
	v_mfma_f32_32x32x16_bf16 v[16:31], v[144:147], v[100:103], v[16:31]
	v_exp_f32_e32 v76, v76
	v_exp_f32_e32 v77, v77
	v_exp_f32_e32 v78, v78
	v_exp_f32_e32 v79, v79
	ds_read_b128 v[124:127], v92 offset:4096
	ds_read_b128 v[120:123], v92 offset:4608
	s_waitcnt lgkmcnt(12)
	v_mfma_f32_32x32x16_bf16 v[0:15], v[136:139], v[104:107], v[0:15]
	v_exp_f32_e32 v48, v48
	v_exp_f32_e32 v49, v49
	v_exp_f32_e32 v50, v50
	v_exp_f32_e32 v51, v51
	ds_read_b128 v[116:119], v92 offset:6144
	ds_read_b128 v[112:115], v92 offset:6656
	s_waitcnt lgkmcnt(12)
	v_mfma_f32_32x32x16_bf16 v[16:31], v[136:139], v[108:111], v[16:31]
	v_exp_f32_e32 v52, v52
	v_exp_f32_e32 v53, v53
	v_exp_f32_e32 v54, v54
	v_exp_f32_e32 v55, v55
	s_waitcnt lgkmcnt(10)
	v_mfma_f32_32x32x16_bf16 v[0:15], v[128:131], v[84:87], v[0:15]
	v_exp_f32_e32 v56, v56
	v_exp_f32_e32 v57, v57
	v_exp_f32_e32 v58, v58
	v_exp_f32_e32 v59, v59
	s_waitcnt lgkmcnt(8)
	v_mfma_f32_32x32x16_bf16 v[16:31], v[128:131], v[88:91], v[16:31]
	v_exp_f32_e32 v60, v60
	v_exp_f32_e32 v61, v61
	v_exp_f32_e32 v62, v62
	v_exp_f32_e32 v63, v63
	s_waitcnt vmcnt(2) lgkmcnt(0)
	s_barrier
	s_add_i32 s20, s44, 0x2000
	s_cmpk_lg_i32 s44, 0x4000
	s_cselect_b32 s21, s20, 0
	s_add_i32 s41, s41, 2
	s_mov_b64 s[30:31], 0x4000
	s_cmp_lt_u32 s41, 57
	v_lshl_add_u64 v[180:181], v[180:181], 0, s[30:31]
	s_cbranch_scc0 .LBB0_401
	s_mov_b32 s20, s42
	s_mov_b32 s43, s44
	s_mov_b32 s42, s21
	s_branch .Lattn_fast_top
	s_nop 0
